# v083 + the 32 short context-query attention units handed out by a ticket counter to the first workgroups that finish their heavy units
# speedup vs baseline: 1.0043x; 1.0001x over previous
; __device__ __forceinline__ void attn_phase_ab(const bf16* P0, const bf16* QB, const bf16* KVB, bf16* OB, const float* aqn, char* lds, const int wave0) {
;     const int c = blockIdx.x, G = gridDim.x;
;     for (int id = c; id < 1024 + 32; id += G) {
;         att::Args a{};
;         int mixer, b, h, qrow0, NT;
;         if (id < 1024) { const int rnd = id >> 8, cc = id & 255; mixer = rnd >> 1; b = rnd & 1; h = cc & 7; qrow0 = b * SEQ + (cc >> 3) * 256; NT = 132; }
;         else { const int cc = id - 1024; mixer = cc >> 4; b = (cc >> 3) & 1; h = cc & 7; qrow0 = MLAT + b * NCTX; NT = 4; }
.LBB0_720:
	s_add_i32 s61, s61, s74
	s_cmpk_lt_i32 s61, 0x400
	s_cbranch_scc1 .LBB0_721
	s_cmp_lg_u32 s93, 0
	s_cbranch_scc1 .Ltick_wait
	s_load_dwordx2 s[6:7], s[0:1], 0xf0
	s_mov_b64 s[4:5], exec
	s_mov_b64 exec, 1
	v_mov_b32_e32 v1, 0x20100
	v_mov_b32_e32 v2, 1
	v_mov_b32_e32 v3, 0
	s_waitcnt lgkmcnt(0)
	s_add_u32 s6, s6, 0x83700
	s_addc_u32 s7, s7, 0
	global_atomic_add v0, v3, v2, s[6:7] sc0
	s_waitcnt vmcnt(0)
	ds_write_b32 v1, v0
	s_waitcnt lgkmcnt(0)
	s_mov_b64 exec, s[4:5]
.Ltick_wait:
	s_barrier
	v_mov_b32_e32 v1, 0x20100
	ds_read_b32 v0, v1
	s_waitcnt lgkmcnt(0)
	v_readfirstlane_b32 s4, v0
	s_barrier
	s_cmp_ge_u32 s4, 32
	s_cbranch_scc1 .LBB0_796
	s_add_i32 s61, s4, 0x400
